# out-proj K-loop: remaining LDS-DMA loads converted to scalar base + lane offset
# baseline (speedup 1.0000x reference)
; #define PG8_STAGE(bufoff, gbase, voff) do { _Pragma("unroll") for (int _i = 0; _i < 2; ++_i) \
;         __builtin_amdgcn_global_load_lds((const unsigned*)((const char*)(gbase) + (voff)[_i]), (LAS unsigned*)(lds + (bufoff) + ldsw + _i * 8192), 16, 0, 0); } while (0)
; #define PG8_LDA(dst, b, h) do { _Pragma("unroll") for (int m = 0; m < 4; ++m) _Pragma("unroll") for (int k = 0; k < 2; ++k) dst[m][k] = *(const LAS bf16x8*)(lds + PG8_SA(b, h) + aoff + m * 2048 + k * 1024); } while (0)
; #define PG8_LDB(dst, b, h) do { _Pragma("unroll") for (int n = 0; n < 2; ++n) _Pragma("unroll") for (int k = 0; k < 2; ++k) dst[n][k] = *(const LAS bf16x8*)(lds + PG8_SB(b, h) + boff + n * 2048 + k * 1024); } while (0)
; #define PG8_MMA(ai, bj, At, Bt) do { __builtin_amdgcn_s_setprio(1); _Pragma("unroll") for (int m = 0; m < 4; ++m) _Pragma("unroll") for (int n = 0; n < 2; ++n) _Pragma("unroll") for (int k = 0; k < 2; ++k) \
;         acc[ai][bj][m][n] = __builtin_amdgcn_mfma_f32_16x16x32_bf16(Bt[n][k], At[m][k], acc[ai][bj][m][n], 0, 0, 0); __builtin_amdgcn_s_setprio(0); } while (0)
; #define PG8_BAR __builtin_amdgcn_s_barrier()
; template <class Epi, class Sched>
; __device__ __forceinline__ void gemm_phase(LAS unsigned char* lds, const Gemm g, const Sched& S, const Epi& E) {
;     ...
;             const bool last = (t == nt - 2);
;             const char* a1 = cA + (size_t)(t + 1) * kstep;
;             const char* a2 = last ? nA : cA + (size_t)(t + 2) * kstep; const char* b2 = last ? nB : cB + (size_t)(t + 2) * kstep;
;             const char* a3 = a2 + kstep; const char* b3 = b2 + kstep;
;             if (last && has_next) S.a_ready(nxt);
;             PG8_LDB(B0, 0, 0); PG8_SCHED; PG8_LDA(At, 0, 0); PG8_STAGE(PG8_SA(1, 1), a1 + hstep, voffA);
;             PG8_WAIT_L(8); PG8_BAR; PG8_WAIT_L(0); PG8_MMA(0, 0, At, B0); PG8_BAR; PG8_SCHED;
;             PG8_LDB(B1, 0, 1); PG8_STAGE(PG8_SB(0, 0), b2, voffB);
;             PG8_BAR; PG8_WAIT_L(0); PG8_MMA(0, 1, At, B1); PG8_BAR;
;             PG8_LDA(At, 0, 1); PG8_STAGE(PG8_SA(0, 0), a2, voffA);
;             PG8_BAR; PG8_WAIT_L(0); PG8_MMA(1, 0, At, B0); PG8_BAR; PG8_SCHED;
;             PG8_STAGE(PG8_SB(0, 1), b2 + hstep, voffB);
;             PG8_WAIT_V(6); PG8_BAR; PG8_MMA(1, 1, At, B1); PG8_BAR;
;             PG8_LDB(B0, 1, 0); PG8_SCHED; PG8_LDA(At, 1, 0); PG8_STAGE(PG8_SA(0, 1), a2 + hstep, voffA);
.LBB0_1123:
	s_nop 0
	v_add_u32_e32 v0, s44, v151
	ds_read_b128 v[138:141], v0
	ds_read_b128 v[142:145], v0 offset:1024
	ds_read_b128 v[146:149], v0 offset:2048
	ds_read_b128 v[154:157], v0 offset:3072
	s_add_u32 s20, s18, 0x100
	s_addc_u32 s21, s19, 0
	s_cmp_eq_u32 s42, 28
	s_cselect_b32 s25, s3, s21
	s_cselect_b32 s24, s9, s20
	s_cselect_b32 s23, s1, s41
	s_cselect_b32 s22, s15, s17
	s_add_i32 m0, s31, 0xc000
	ds_read_b128 v[158:161], v153
	ds_read_b128 v[162:165], v153 offset:1024
	ds_read_b128 v[166:169], v153 offset:2048
	ds_read_b128 v[170:173], v153 offset:3072
	ds_read_b128 v[174:177], v153 offset:4096
	ds_read_b128 v[178:181], v153 offset:5120
	ds_read_b128 v[182:185], v153 offset:6144
	ds_read_b128 v[186:189], v153 offset:7168
	global_load_lds_dwordx4 v134, s[18:19]
	s_add_i32 m0, s31, 0xe000
	s_nop 0
	global_load_lds_dwordx4 v136, s[18:19]
	s_waitcnt lgkmcnt(8)
	s_barrier
	s_waitcnt lgkmcnt(0)
	v_mfma_f32_16x16x32_bf16 v[126:129], v[138:141], v[158:161], v[126:129]
	v_mfma_f32_16x16x32_bf16 v[122:125], v[146:149], v[158:161], v[122:125]
	v_mfma_f32_16x16x32_bf16 v[110:113], v[138:141], v[166:169], v[110:113]
	v_mfma_f32_16x16x32_bf16 v[106:109], v[146:149], v[166:169], v[106:109]
	v_mfma_f32_16x16x32_bf16 v[94:97], v[138:141], v[174:177], v[94:97]
	v_mfma_f32_16x16x32_bf16 v[90:93], v[146:149], v[174:177], v[90:93]
	v_mfma_f32_16x16x32_bf16 v[78:81], v[138:141], v[182:185], v[78:81]
	v_mfma_f32_16x16x32_bf16 v[74:77], v[146:149], v[182:185], v[74:77]
	v_mfma_f32_16x16x32_bf16 v[126:129], v[142:145], v[162:165], v[126:129]
	v_mfma_f32_16x16x32_bf16 v[122:125], v[154:157], v[162:165], v[122:125]
	v_mfma_f32_16x16x32_bf16 v[110:113], v[142:145], v[170:173], v[110:113]
	v_mfma_f32_16x16x32_bf16 v[106:109], v[154:157], v[170:173], v[106:109]
	v_mfma_f32_16x16x32_bf16 v[94:97], v[142:145], v[178:181], v[94:97]
	v_mfma_f32_16x16x32_bf16 v[90:93], v[154:157], v[178:181], v[90:93]
	v_mfma_f32_16x16x32_bf16 v[78:81], v[142:145], v[186:189], v[78:81]
	v_mfma_f32_16x16x32_bf16 v[74:77], v[154:157], v[186:189], v[74:77]
	s_barrier
	s_add_i32 s43, 0, 0x14000
	s_add_i32 s18, s44, s30
	v_add_u32_e32 v0, s43, v151
	s_mov_b32 m0, s18
	ds_read_b128 v[190:193], v0
	ds_read_b128 v[194:197], v0 offset:1024
	ds_read_b128 v[198:201], v0 offset:2048
	ds_read_b128 v[202:205], v0 offset:3072
	global_load_lds_dwordx4 v130, s[22:23]
	s_add_i32 m0, s18, 0x2000
	s_nop 0
	global_load_lds_dwordx4 v132, s[22:23]
	s_barrier
	s_waitcnt lgkmcnt(0)
	v_mfma_f32_16x16x32_bf16 v[118:121], v[190:193], v[158:161], v[118:121]
	v_mfma_f32_16x16x32_bf16 v[114:117], v[198:201], v[158:161], v[114:117]
	v_mfma_f32_16x16x32_bf16 v[102:105], v[190:193], v[166:169], v[102:105]
	v_mfma_f32_16x16x32_bf16 v[98:101], v[198:201], v[166:169], v[98:101]
	v_mfma_f32_16x16x32_bf16 v[86:89], v[190:193], v[174:177], v[86:89]
	v_mfma_f32_16x16x32_bf16 v[82:85], v[198:201], v[174:177], v[82:85]
	v_mfma_f32_16x16x32_bf16 v[70:73], v[190:193], v[182:185], v[70:73]
	v_mfma_f32_16x16x32_bf16 v[66:69], v[198:201], v[182:185], v[66:69]
	v_mfma_f32_16x16x32_bf16 v[118:121], v[194:197], v[162:165], v[118:121]
	v_mfma_f32_16x16x32_bf16 v[114:117], v[202:205], v[162:165], v[114:117]
	v_mfma_f32_16x16x32_bf16 v[102:105], v[194:197], v[170:173], v[102:105]
	v_mfma_f32_16x16x32_bf16 v[98:101], v[202:205], v[170:173], v[98:101]
	v_mfma_f32_16x16x32_bf16 v[86:89], v[194:197], v[178:181], v[86:89]
	v_mfma_f32_16x16x32_bf16 v[82:85], v[202:205], v[178:181], v[82:85]
	v_mfma_f32_16x16x32_bf16 v[70:73], v[194:197], v[186:189], v[70:73]
	v_mfma_f32_16x16x32_bf16 v[66:69], v[202:205], v[186:189], v[66:69]
	s_mov_b32 m0, s31
	s_add_u32 s46, s24, 0x80
	s_addc_u32 s47, s25, 0
	s_barrier
	ds_read_b128 v[158:161], v153 offset:16384
	ds_read_b128 v[162:165], v153 offset:17408
	ds_read_b128 v[166:169], v153 offset:18432
	ds_read_b128 v[170:173], v153 offset:19456
	ds_read_b128 v[174:177], v153 offset:20480
	ds_read_b128 v[178:181], v153 offset:21504
	ds_read_b128 v[182:185], v153 offset:22528
	ds_read_b128 v[186:189], v153 offset:23552
	global_load_lds_dwordx4 v130, s[24:25]
	s_mov_b32 m0, s34
	s_nop 0
	global_load_lds_dwordx4 v132, s[24:25]
	s_barrier
	s_waitcnt lgkmcnt(0)
	v_mfma_f32_16x16x32_bf16 v[62:65], v[138:141], v[158:161], v[62:65]
	v_mfma_f32_16x16x32_bf16 v[58:61], v[146:149], v[158:161], v[58:61]
	v_mfma_f32_16x16x32_bf16 v[46:49], v[138:141], v[166:169], v[46:49]
	v_mfma_f32_16x16x32_bf16 v[42:45], v[146:149], v[166:169], v[42:45]
	v_mfma_f32_16x16x32_bf16 v[30:33], v[138:141], v[174:177], v[30:33]
	v_mfma_f32_16x16x32_bf16 v[26:29], v[146:149], v[174:177], v[26:29]
	v_mfma_f32_16x16x32_bf16 v[14:17], v[138:141], v[182:185], v[14:17]
	v_mfma_f32_16x16x32_bf16 v[10:13], v[146:149], v[182:185], v[10:13]
	v_mfma_f32_16x16x32_bf16 v[62:65], v[142:145], v[162:165], v[62:65]
	v_mfma_f32_16x16x32_bf16 v[58:61], v[154:157], v[162:165], v[58:61]
	v_mfma_f32_16x16x32_bf16 v[46:49], v[142:145], v[170:173], v[46:49]
	v_mfma_f32_16x16x32_bf16 v[42:45], v[154:157], v[170:173], v[42:45]
	v_mfma_f32_16x16x32_bf16 v[30:33], v[142:145], v[178:181], v[30:33]
	v_mfma_f32_16x16x32_bf16 v[26:29], v[154:157], v[178:181], v[26:29]
	v_mfma_f32_16x16x32_bf16 v[14:17], v[142:145], v[186:189], v[14:17]
	v_mfma_f32_16x16x32_bf16 v[10:13], v[154:157], v[186:189], v[10:13]
	s_barrier
	s_add_u32 s18, s22, 0x80000
	s_addc_u32 s19, s23, 0
	s_add_i32 s43, s43, s30
	s_mov_b32 m0, s43
	s_nop 0
	global_load_lds_dwordx4 v130, s[18:19]
	s_add_i32 m0, s43, 0x2000
	s_nop 0
	global_load_lds_dwordx4 v132, s[18:19]
	s_waitcnt vmcnt(6)
	s_barrier
; #define PG8_STAGE(bufoff, gbase, voff) do { _Pragma("unroll") for (int _i = 0; _i < 2; ++_i) \
;         __builtin_amdgcn_global_load_lds((const unsigned*)((const char*)(gbase) + (voff)[_i]), (LAS unsigned*)(lds + (bufoff) + ldsw + _i * 8192), 16, 0, 0); } while (0)
; #define PG8_LDA(dst, b, h) do { _Pragma("unroll") for (int m = 0; m < 4; ++m) _Pragma("unroll") for (int k = 0; k < 2; ++k) dst[m][k] = *(const LAS bf16x8*)(lds + PG8_SA(b, h) + aoff + m * 2048 + k * 1024); } while (0)
; #define PG8_LDB(dst, b, h) do { _Pragma("unroll") for (int n = 0; n < 2; ++n) _Pragma("unroll") for (int k = 0; k < 2; ++k) dst[n][k] = *(const LAS bf16x8*)(lds + PG8_SB(b, h) + boff + n * 2048 + k * 1024); } while (0)
; #define PG8_MMA(ai, bj, At, Bt) do { __builtin_amdgcn_s_setprio(1); _Pragma("unroll") for (int m = 0; m < 4; ++m) _Pragma("unroll") for (int n = 0; n < 2; ++n) _Pragma("unroll") for (int k = 0; k < 2; ++k) \
;         acc[ai][bj][m][n] = __builtin_amdgcn_mfma_f32_16x16x32_bf16(Bt[n][k], At[m][k], acc[ai][bj][m][n], 0, 0, 0); __builtin_amdgcn_s_setprio(0); } while (0)
; #define PG8_WAIT_V(n) asm volatile("s_waitcnt vmcnt(" #n ")" ::: "memory")
; #define PG8_WAIT_L(n) asm volatile("s_waitcnt lgkmcnt(" #n ")" ::: "memory")
; #define PG8_BAR __builtin_amdgcn_s_barrier()
; #define PG8_SCHED __builtin_amdgcn_sched_barrier(0)
; template <class Epi, class Sched>
; __device__ __forceinline__ void gemm_phase(LAS unsigned char* lds, const Gemm g, const Sched& S, const Epi& E) {
;     ...
;             PG8_WAIT_V(6); PG8_BAR; PG8_MMA(1, 1, At, B1); PG8_BAR;
;             PG8_LDB(B0, 1, 0); PG8_SCHED; PG8_LDA(At, 1, 0); PG8_STAGE(PG8_SA(0, 1), a2 + hstep, voffA);
;             PG8_WAIT_L(8); PG8_BAR; PG8_WAIT_L(0); PG8_MMA(0, 0, At, B0); PG8_BAR; PG8_SCHED;
;             PG8_LDB(B1, 1, 1); PG8_STAGE(PG8_SB(1, 0), b3, voffB);
;             PG8_BAR; PG8_WAIT_L(0); PG8_MMA(0, 1, At, B1); PG8_BAR;
;             PG8_LDA(At, 1, 1); PG8_STAGE(PG8_SA(1, 0), a3, voffA);
	v_mfma_f32_16x16x32_bf16 v[54:57], v[190:193], v[158:161], v[54:57]
	v_mfma_f32_16x16x32_bf16 v[50:53], v[198:201], v[158:161], v[50:53]
	v_mfma_f32_16x16x32_bf16 v[38:41], v[190:193], v[166:169], v[38:41]
	v_mfma_f32_16x16x32_bf16 v[34:37], v[198:201], v[166:169], v[34:37]
	v_mfma_f32_16x16x32_bf16 v[22:25], v[190:193], v[174:177], v[22:25]
	v_mfma_f32_16x16x32_bf16 v[18:21], v[198:201], v[174:177], v[18:21]
	v_mfma_f32_16x16x32_bf16 v[6:9], v[190:193], v[182:185], v[6:9]
	v_mfma_f32_16x16x32_bf16 v[2:5], v[198:201], v[182:185], v[2:5]
	v_mfma_f32_16x16x32_bf16 v[54:57], v[194:197], v[162:165], v[54:57]
	v_mfma_f32_16x16x32_bf16 v[50:53], v[202:205], v[162:165], v[50:53]
	v_mfma_f32_16x16x32_bf16 v[38:41], v[194:197], v[170:173], v[38:41]
	v_mfma_f32_16x16x32_bf16 v[34:37], v[202:205], v[170:173], v[34:37]
	v_mfma_f32_16x16x32_bf16 v[22:25], v[194:197], v[178:181], v[22:25]
	v_mfma_f32_16x16x32_bf16 v[18:21], v[202:205], v[178:181], v[18:21]
	v_mfma_f32_16x16x32_bf16 v[6:9], v[194:197], v[186:189], v[6:9]
	v_mfma_f32_16x16x32_bf16 v[2:5], v[202:205], v[186:189], v[2:5]
	s_add_i32 s43, 0, 0x18000
	v_add_u32_e32 v0, s43, v151
	s_barrier
	ds_read_b128 v[138:141], v0
	ds_read_b128 v[142:145], v0 offset:1024
	ds_read_b128 v[146:149], v0 offset:2048
	ds_read_b128 v[154:157], v0 offset:3072
	s_add_u32 s18, s24, 0x80000
	s_addc_u32 s19, s25, 0
	s_mov_b32 m0, s35
	ds_read_b128 v[158:161], v153 offset:32768
	ds_read_b128 v[162:165], v153 offset:33792
	ds_read_b128 v[166:169], v153 offset:34816
	ds_read_b128 v[170:173], v153 offset:35840
	ds_read_b128 v[174:177], v153 offset:36864
	ds_read_b128 v[178:181], v153 offset:37888
	ds_read_b128 v[182:185], v153 offset:38912
	ds_read_b128 v[186:189], v153 offset:39936
	global_load_lds_dwordx4 v130, s[18:19]
	s_mov_b32 m0, s36
	s_nop 0
	global_load_lds_dwordx4 v132, s[18:19]
	s_waitcnt lgkmcnt(8)
	s_barrier
	s_waitcnt lgkmcnt(0)
	v_mfma_f32_16x16x32_bf16 v[126:129], v[138:141], v[158:161], v[126:129]
	v_mfma_f32_16x16x32_bf16 v[122:125], v[146:149], v[158:161], v[122:125]
	v_mfma_f32_16x16x32_bf16 v[110:113], v[138:141], v[166:169], v[110:113]
	v_mfma_f32_16x16x32_bf16 v[106:109], v[146:149], v[166:169], v[106:109]
	v_mfma_f32_16x16x32_bf16 v[94:97], v[138:141], v[174:177], v[94:97]
	v_mfma_f32_16x16x32_bf16 v[90:93], v[146:149], v[174:177], v[90:93]
	v_mfma_f32_16x16x32_bf16 v[78:81], v[138:141], v[182:185], v[78:81]
	v_mfma_f32_16x16x32_bf16 v[74:77], v[146:149], v[182:185], v[74:77]
	v_mfma_f32_16x16x32_bf16 v[126:129], v[142:145], v[162:165], v[126:129]
	v_mfma_f32_16x16x32_bf16 v[122:125], v[154:157], v[162:165], v[122:125]
	v_mfma_f32_16x16x32_bf16 v[110:113], v[142:145], v[170:173], v[110:113]
	v_mfma_f32_16x16x32_bf16 v[106:109], v[154:157], v[170:173], v[106:109]
	v_mfma_f32_16x16x32_bf16 v[94:97], v[142:145], v[178:181], v[94:97]
	v_mfma_f32_16x16x32_bf16 v[90:93], v[154:157], v[178:181], v[90:93]
	v_mfma_f32_16x16x32_bf16 v[78:81], v[142:145], v[186:189], v[78:81]
	v_mfma_f32_16x16x32_bf16 v[74:77], v[154:157], v[186:189], v[74:77]
	s_barrier
	s_add_i32 s24, 0, 0x1c000
	s_add_i32 s18, s43, s30
	v_add_u32_e32 v0, s24, v151
	s_add_u32 s48, s22, 0x80
	s_addc_u32 s49, s23, 0
	s_mov_b32 m0, s18
	ds_read_b128 v[190:193], v0
	ds_read_b128 v[194:197], v0 offset:1024
	ds_read_b128 v[198:201], v0 offset:2048
	ds_read_b128 v[202:205], v0 offset:3072
	global_load_lds_dwordx4 v130, s[48:49]
	s_add_i32 m0, s18, 0x2000
	s_nop 0
	global_load_lds_dwordx4 v132, s[48:49]
	s_barrier
	s_waitcnt lgkmcnt(0)
	v_mfma_f32_16x16x32_bf16 v[118:121], v[190:193], v[158:161], v[118:121]
	v_mfma_f32_16x16x32_bf16 v[114:117], v[198:201], v[158:161], v[114:117]
	v_mfma_f32_16x16x32_bf16 v[102:105], v[190:193], v[166:169], v[102:105]
	v_mfma_f32_16x16x32_bf16 v[98:101], v[198:201], v[166:169], v[98:101]
	v_mfma_f32_16x16x32_bf16 v[86:89], v[190:193], v[174:177], v[86:89]
	v_mfma_f32_16x16x32_bf16 v[82:85], v[198:201], v[174:177], v[82:85]
	v_mfma_f32_16x16x32_bf16 v[70:73], v[190:193], v[182:185], v[70:73]
	v_mfma_f32_16x16x32_bf16 v[66:69], v[198:201], v[182:185], v[66:69]
	v_mfma_f32_16x16x32_bf16 v[118:121], v[194:197], v[162:165], v[118:121]
	v_mfma_f32_16x16x32_bf16 v[114:117], v[202:205], v[162:165], v[114:117]
	v_mfma_f32_16x16x32_bf16 v[102:105], v[194:197], v[170:173], v[102:105]
	v_mfma_f32_16x16x32_bf16 v[98:101], v[202:205], v[170:173], v[98:101]
	v_mfma_f32_16x16x32_bf16 v[86:89], v[194:197], v[178:181], v[86:89]
	v_mfma_f32_16x16x32_bf16 v[82:85], v[202:205], v[178:181], v[82:85]
	v_mfma_f32_16x16x32_bf16 v[70:73], v[194:197], v[186:189], v[70:73]
	v_mfma_f32_16x16x32_bf16 v[66:69], v[202:205], v[186:189], v[66:69]
	s_mov_b32 m0, s38
	s_barrier
	ds_read_b128 v[158:161], v153 offset:49152
	ds_read_b128 v[162:165], v153 offset:50176
	ds_read_b128 v[166:169], v153 offset:51200
	ds_read_b128 v[170:173], v153 offset:52224
	ds_read_b128 v[174:177], v153 offset:53248
	ds_read_b128 v[178:181], v153 offset:54272
	ds_read_b128 v[182:185], v153 offset:55296
	ds_read_b128 v[186:189], v153 offset:56320
	global_load_lds_dwordx4 v130, s[46:47]
	s_mov_b32 m0, s39
	s_nop 0
	global_load_lds_dwordx4 v132, s[46:47]
	s_barrier
; #define PG8_STAGE(bufoff, gbase, voff) do { _Pragma("unroll") for (int _i = 0; _i < 2; ++_i) \
;         __builtin_amdgcn_global_load_lds((const unsigned*)((const char*)(gbase) + (voff)[_i]), (LAS unsigned*)(lds + (bufoff) + ldsw + _i * 8192), 16, 0, 0); } while (0)
; #define PG8_MMA(ai, bj, At, Bt) do { __builtin_amdgcn_s_setprio(1); _Pragma("unroll") for (int m = 0; m < 4; ++m) _Pragma("unroll") for (int n = 0; n < 2; ++n) _Pragma("unroll") for (int k = 0; k < 2; ++k) \
;         acc[ai][bj][m][n] = __builtin_amdgcn_mfma_f32_16x16x32_bf16(Bt[n][k], At[m][k], acc[ai][bj][m][n], 0, 0, 0); __builtin_amdgcn_s_setprio(0); } while (0)
; #define PG8_WAIT_V(n) asm volatile("s_waitcnt vmcnt(" #n ")" ::: "memory")
; #define PG8_WAIT_L(n) asm volatile("s_waitcnt lgkmcnt(" #n ")" ::: "memory")
; #define PG8_BAR __builtin_amdgcn_s_barrier()
; #define PG8_SCHED __builtin_amdgcn_sched_barrier(0)
; template <class Epi, class Sched>
; __device__ __forceinline__ void gemm_phase(LAS unsigned char* lds, const Gemm g, const Sched& S, const Epi& E) {
;     ...
;             PG8_BAR; PG8_WAIT_L(0); PG8_MMA(1, 0, At, B0); PG8_BAR; PG8_SCHED;
;             PG8_STAGE(PG8_SB(1, 1), b3 + hstep, voffB);
;             PG8_WAIT_V(6); PG8_BAR; PG8_MMA(1, 1, At, B1); PG8_BAR;
;     __device__ __forceinline__ void operator()(const f32x4 (&acc)[2][2][4][2], const pg8::Unit& u, int wr, int wc, int fr, int fq) const {
;         const int row0 = u.pm * 256 + wr * 64 + fr; const int col0 = u.pn * 256 + wc * 32 + 4 * fq;
; #pragma unroll
;         for (int ai = 0; ai < 2; ++ai)
; #pragma unroll
;             for (int m = 0; m < 4; ++m) { const int row = row0 + ai * 128 + m * 16;
;                 const float* ip; float* op; int b;
;                 if (row < ML_ROWS) { b = row >> 11; ip = xi + (size_t)row * D; op = xo + (size_t)row * D; }
;                 else { b = 8; ip = ci + (size_t)(row - ML_ROWS) * D; op = co + (size_t)(row - ML_ROWS) * D; }
;                 const float* gp = mod + (size_t)b * 12288 + slot * 2048;
; #pragma unroll
;                 for (int bj = 0; bj < 2; ++bj)
; #pragma unroll
;                     for (int n = 0; n < 2; ++n) { const int c = col0 + bj * 128 + n * 16;
;                         const f32x4 r = *(const f32x4*)(ip + c), g = *(const f32x4*)(gp + c);
;                         *(f32x4*)(op + c) = r + g * acc[ai][bj][m][n]; } }
	s_waitcnt lgkmcnt(0)
	v_mfma_f32_16x16x32_bf16 v[62:65], v[138:141], v[158:161], v[62:65]
	v_mfma_f32_16x16x32_bf16 v[58:61], v[146:149], v[158:161], v[58:61]
	v_mfma_f32_16x16x32_bf16 v[46:49], v[138:141], v[166:169], v[46:49]
	v_mfma_f32_16x16x32_bf16 v[42:45], v[146:149], v[166:169], v[42:45]
	v_mfma_f32_16x16x32_bf16 v[30:33], v[138:141], v[174:177], v[30:33]
	v_mfma_f32_16x16x32_bf16 v[26:29], v[146:149], v[174:177], v[26:29]
	v_mfma_f32_16x16x32_bf16 v[14:17], v[138:141], v[182:185], v[14:17]
	v_mfma_f32_16x16x32_bf16 v[10:13], v[146:149], v[182:185], v[10:13]
	v_mfma_f32_16x16x32_bf16 v[62:65], v[142:145], v[162:165], v[62:65]
	v_mfma_f32_16x16x32_bf16 v[58:61], v[154:157], v[162:165], v[58:61]
	v_mfma_f32_16x16x32_bf16 v[46:49], v[142:145], v[170:173], v[46:49]
	v_mfma_f32_16x16x32_bf16 v[42:45], v[154:157], v[170:173], v[42:45]
	v_mfma_f32_16x16x32_bf16 v[30:33], v[142:145], v[178:181], v[30:33]
	v_mfma_f32_16x16x32_bf16 v[26:29], v[154:157], v[178:181], v[26:29]
	v_mfma_f32_16x16x32_bf16 v[14:17], v[142:145], v[186:189], v[14:17]
	v_mfma_f32_16x16x32_bf16 v[10:13], v[154:157], v[186:189], v[10:13]
	s_barrier
	s_add_u32 s18, s22, 0x80080
	s_addc_u32 s19, s23, 0
	s_add_i32 s22, s24, s30
	s_mov_b32 m0, s22
	s_nop 0
	global_load_lds_dwordx4 v130, s[18:19]
	s_add_i32 m0, s22, 0x2000
	s_nop 0
	global_load_lds_dwordx4 v132, s[18:19]
	s_waitcnt vmcnt(6)
	s_barrier
	v_mfma_f32_16x16x32_bf16 v[54:57], v[190:193], v[158:161], v[54:57]
	v_mfma_f32_16x16x32_bf16 v[50:53], v[198:201], v[158:161], v[50:53]
	v_mfma_f32_16x16x32_bf16 v[38:41], v[190:193], v[166:169], v[38:41]
	v_mfma_f32_16x16x32_bf16 v[34:37], v[198:201], v[166:169], v[34:37]
	v_mfma_f32_16x16x32_bf16 v[22:25], v[190:193], v[174:177], v[22:25]
	v_mfma_f32_16x16x32_bf16 v[18:21], v[198:201], v[174:177], v[18:21]
	v_mfma_f32_16x16x32_bf16 v[6:9], v[190:193], v[182:185], v[6:9]
	v_mfma_f32_16x16x32_bf16 v[2:5], v[198:201], v[182:185], v[2:5]
	v_mfma_f32_16x16x32_bf16 v[54:57], v[194:197], v[162:165], v[54:57]
	v_mfma_f32_16x16x32_bf16 v[50:53], v[202:205], v[162:165], v[50:53]
	v_mfma_f32_16x16x32_bf16 v[38:41], v[194:197], v[170:173], v[38:41]
	v_mfma_f32_16x16x32_bf16 v[34:37], v[202:205], v[170:173], v[34:37]
	v_mfma_f32_16x16x32_bf16 v[22:25], v[194:197], v[178:181], v[22:25]
	v_mfma_f32_16x16x32_bf16 v[18:21], v[202:205], v[178:181], v[18:21]
	v_mfma_f32_16x16x32_bf16 v[6:9], v[194:197], v[186:189], v[6:9]
	v_mfma_f32_16x16x32_bf16 v[2:5], v[202:205], v[186:189], v[2:5]
	s_add_i32 s42, s42, 2
	s_add_u32 s17, s17, 0x100
	s_addc_u32 s41, s41, 0
	s_cmp_gt_u32 s42, 29
	s_mov_b64 s[18:19], s[20:21]
	s_barrier
	s_cbranch_scc0 .LBB0_1123
	s_lshl_b32 s1, s16, 8
	s_add_i32 s1, s1, s37
	v_readlane_b32 s44, v251, 0
	v_readlane_b32 s45, v251, 1
	v_readlane_b32 s46, v251, 2
	v_readlane_b32 s47, v251, 3
	v_readlane_b32 s48, v251, 4
	v_readlane_b32 s49, v251, 5
	v_readlane_b32 s50, v251, 6
	v_readlane_b32 s51, v251, 7
	v_readlane_b32 s22, v254, 4
	v_readlane_b32 s23, v254, 5
	v_readlane_b32 s20, v254, 6
	v_readlane_b32 s21, v254, 7
	v_readlane_b32 s18, v254, 2
	v_readlane_b32 s19, v254, 3
	s_add_i32 s3, s1, 0xffffc000
	s_ashr_i32 s15, s1, 11
	s_cmpk_lt_i32 s1, 0x4000
	s_cselect_b32 s22, s22, s20
	s_cselect_b32 s23, s23, s21
	s_cselect_b32 s20, s46, s60
	s_cselect_b32 s21, s47, s61
	s_cselect_b32 s3, s1, s3
	s_cselect_b32 s15, s15, 8
	s_mul_i32 s15, s15, 0xc000
	s_add_u32 s18, s18, s15
	s_addc_u32 s19, s19, 0
	s_add_u32 s18, s18, 0x4000
	s_addc_u32 s19, s19, 0
	v_add_u32_e32 v138, s3, v150
	v_lshl_or_b32 v139, s14, 8, v152
	v_lshlrev_b32_e32 v139, 2, v139
	v_lshl_or_b32 v138, v138, 13, v139
	v_add_u32_e32 v140, 0x20000, v138
	v_add_u32_e32 v141, 0x40000, v138
	v_add_u32_e32 v0, 0x60000, v138
	v_add_u32_e32 v210, 0x100000, v138
	v_add_u32_e32 v211, 0x120000, v138
	v_add_u32_e32 v220, 0x140000, v138
	global_load_dwordx4 v[154:157], v139, s[18:19]
	global_load_dwordx4 v[158:161], v139, s[18:19] offset:64
	global_load_dwordx4 v[162:165], v139, s[18:19] offset:512
	global_load_dwordx4 v[166:169], v139, s[18:19] offset:576
	v_add_u32_e32 v139, 0x160000, v138
	global_load_dwordx4 v[170:173], v138, s[22:23]
	global_load_dwordx4 v[174:177], v138, s[22:23] offset:64
	global_load_dwordx4 v[178:181], v138, s[22:23] offset:512
	global_load_dwordx4 v[182:185], v138, s[22:23] offset:576
	global_load_dwordx4 v[186:189], v140, s[22:23]
	global_load_dwordx4 v[190:193], v140, s[22:23] offset:64
	global_load_dwordx4 v[194:197], v140, s[22:23] offset:512
	global_load_dwordx4 v[198:201], v140, s[22:23] offset:576
	global_load_dwordx4 v[202:205], v141, s[22:23]
	global_load_dwordx4 v[206:209], v141, s[22:23] offset:64
	global_load_dwordx4 v[142:145], v141, s[22:23] offset:512
	global_load_dwordx4 v[146:149], v141, s[22:23] offset:576
	s_waitcnt vmcnt(8)
	v_pk_fma_f32 v[126:127], v[126:127], v[154:155], v[170:171]
	v_pk_fma_f32 v[128:129], v[128:129], v[156:157], v[172:173]
	v_pk_fma_f32 v[122:123], v[122:123], v[158:159], v[174:175]
	v_pk_fma_f32 v[124:125], v[124:125], v[160:161], v[176:177]
	v_pk_fma_f32 v[118:119], v[118:119], v[162:163], v[178:179]
	v_pk_fma_f32 v[120:121], v[120:121], v[164:165], v[180:181]
	v_pk_fma_f32 v[114:115], v[114:115], v[166:167], v[182:183]
	v_pk_fma_f32 v[116:117], v[116:117], v[168:169], v[184:185]
	global_store_dwordx4 v138, v[126:129], s[20:21]
	global_store_dwordx4 v138, v[122:125], s[20:21] offset:64
	global_store_dwordx4 v138, v[118:121], s[20:21] offset:512
	global_store_dwordx4 v138, v[114:117], s[20:21] offset:576
	global_load_dwordx4 v[170:173], v0, s[22:23]
	global_load_dwordx4 v[174:177], v0, s[22:23] offset:64
	global_load_dwordx4 v[178:181], v0, s[22:23] offset:512
	global_load_dwordx4 v[182:185], v0, s[22:23] offset:576
	s_waitcnt vmcnt(12)
; template <class Epi, class Sched>
; __device__ __forceinline__ void gemm_phase(LAS unsigned char* lds, const Gemm g, const Sched& S, const Epi& E) {
;     ...
;         E(acc, cur, wr, wc, fr, fq); S.done(cur);
;         if (!has_next) break;
; #pragma unroll
;         for (int a = 0; a < 2; ++a)
; #pragma unroll
;             for (int b = 0; b < 2; ++b)
; #pragma unroll
;                 for (int m = 0; m < 4; ++m)
; #pragma unroll
;                     for (int n = 0; n < 2; ++n) acc[a][b][m][n] = (f32x4){0.f, 0.f, 0.f, 0.f};
;         cur = nxt; cA = nA; cB = nB; ++ui;
;     __device__ __forceinline__ void operator()(const f32x4 (&acc)[2][2][4][2], const pg8::Unit& u, int wr, int wc, int fr, int fq) const {
;     ...
;             for (int m = 0; m < 4; ++m) { const int row = row0 + ai * 128 + m * 16;
;                 const float* ip; float* op; int b;
;                 if (row < ML_ROWS) { b = row >> 11; ip = xi + (size_t)row * D; op = xo + (size_t)row * D; }
;                 else { b = 8; ip = ci + (size_t)(row - ML_ROWS) * D; op = co + (size_t)(row - ML_ROWS) * D; }
;                 const float* gp = mod + (size_t)b * 12288 + slot * 2048;
; #pragma unroll
;                 for (int bj = 0; bj < 2; ++bj)
; #pragma unroll
;                     for (int n = 0; n < 2; ++n) { const int c = col0 + bj * 128 + n * 16;
;                         const f32x4 r = *(const f32x4*)(ip + c), g = *(const f32x4*)(gp + c);
;                         *(f32x4*)(op + c) = r + g * acc[ai][bj][m][n]; } }
	v_pk_fma_f32 v[110:111], v[110:111], v[154:155], v[186:187]
	v_pk_fma_f32 v[112:113], v[112:113], v[156:157], v[188:189]
	v_pk_fma_f32 v[106:107], v[106:107], v[158:159], v[190:191]
	v_pk_fma_f32 v[108:109], v[108:109], v[160:161], v[192:193]
	v_pk_fma_f32 v[102:103], v[102:103], v[162:163], v[194:195]
	v_pk_fma_f32 v[104:105], v[104:105], v[164:165], v[196:197]
	v_pk_fma_f32 v[98:99], v[98:99], v[166:167], v[198:199]
	v_pk_fma_f32 v[100:101], v[100:101], v[168:169], v[200:201]
	global_store_dwordx4 v140, v[110:113], s[20:21]
	global_store_dwordx4 v140, v[106:109], s[20:21] offset:64
	global_store_dwordx4 v140, v[102:105], s[20:21] offset:512
	global_store_dwordx4 v140, v[98:101], s[20:21] offset:576
	global_load_dwordx4 v[186:189], v210, s[22:23]
	global_load_dwordx4 v[190:193], v210, s[22:23] offset:64
	global_load_dwordx4 v[194:197], v210, s[22:23] offset:512
	global_load_dwordx4 v[198:201], v210, s[22:23] offset:576
	s_waitcnt vmcnt(16)
	v_pk_fma_f32 v[94:95], v[94:95], v[154:155], v[202:203]
	v_pk_fma_f32 v[96:97], v[96:97], v[156:157], v[204:205]
	v_pk_fma_f32 v[90:91], v[90:91], v[158:159], v[206:207]
	v_pk_fma_f32 v[92:93], v[92:93], v[160:161], v[208:209]
	v_pk_fma_f32 v[86:87], v[86:87], v[162:163], v[142:143]
	v_pk_fma_f32 v[88:89], v[88:89], v[164:165], v[144:145]
	v_pk_fma_f32 v[82:83], v[82:83], v[166:167], v[146:147]
	v_pk_fma_f32 v[84:85], v[84:85], v[168:169], v[148:149]
	global_store_dwordx4 v141, v[94:97], s[20:21]
	global_store_dwordx4 v141, v[90:93], s[20:21] offset:64
	global_store_dwordx4 v141, v[86:89], s[20:21] offset:512
	global_store_dwordx4 v141, v[82:85], s[20:21] offset:576
	global_load_dwordx4 v[202:205], v211, s[22:23]
	global_load_dwordx4 v[206:209], v211, s[22:23] offset:64
	global_load_dwordx4 v[142:145], v211, s[22:23] offset:512
	global_load_dwordx4 v[146:149], v211, s[22:23] offset:576
	s_waitcnt vmcnt(16)
	v_pk_fma_f32 v[78:79], v[78:79], v[154:155], v[170:171]
	v_pk_fma_f32 v[80:81], v[80:81], v[156:157], v[172:173]
	v_pk_fma_f32 v[74:75], v[74:75], v[158:159], v[174:175]
	v_pk_fma_f32 v[76:77], v[76:77], v[160:161], v[176:177]
	v_pk_fma_f32 v[70:71], v[70:71], v[162:163], v[178:179]
	v_pk_fma_f32 v[72:73], v[72:73], v[164:165], v[180:181]
	v_pk_fma_f32 v[66:67], v[66:67], v[166:167], v[182:183]
	v_pk_fma_f32 v[68:69], v[68:69], v[168:169], v[184:185]
	global_store_dwordx4 v0, v[78:81], s[20:21]
	global_store_dwordx4 v0, v[74:77], s[20:21] offset:64
	global_store_dwordx4 v0, v[70:73], s[20:21] offset:512
	global_store_dwordx4 v0, v[66:69], s[20:21] offset:576
	global_load_dwordx4 v[170:173], v220, s[22:23]
	global_load_dwordx4 v[174:177], v220, s[22:23] offset:64
	global_load_dwordx4 v[178:181], v220, s[22:23] offset:512
	global_load_dwordx4 v[182:185], v220, s[22:23] offset:576
	s_waitcnt vmcnt(16)
	v_pk_fma_f32 v[62:63], v[62:63], v[154:155], v[186:187]
	v_pk_fma_f32 v[64:65], v[64:65], v[156:157], v[188:189]
	v_pk_fma_f32 v[58:59], v[58:59], v[158:159], v[190:191]
	v_pk_fma_f32 v[60:61], v[60:61], v[160:161], v[192:193]
	v_pk_fma_f32 v[54:55], v[54:55], v[162:163], v[194:195]
	v_pk_fma_f32 v[56:57], v[56:57], v[164:165], v[196:197]
	v_pk_fma_f32 v[50:51], v[50:51], v[166:167], v[198:199]
	v_pk_fma_f32 v[52:53], v[52:53], v[168:169], v[200:201]
	global_store_dwordx4 v210, v[62:65], s[20:21]
	global_store_dwordx4 v210, v[58:61], s[20:21] offset:64
	global_store_dwordx4 v210, v[54:57], s[20:21] offset:512
	global_store_dwordx4 v210, v[50:53], s[20:21] offset:576
	global_load_dwordx4 v[186:189], v139, s[22:23]
	global_load_dwordx4 v[190:193], v139, s[22:23] offset:64
	global_load_dwordx4 v[194:197], v139, s[22:23] offset:512
	global_load_dwordx4 v[198:201], v139, s[22:23] offset:576
	s_waitcnt vmcnt(16)
	v_pk_fma_f32 v[46:47], v[46:47], v[154:155], v[202:203]
	v_pk_fma_f32 v[48:49], v[48:49], v[156:157], v[204:205]
	v_pk_fma_f32 v[42:43], v[42:43], v[158:159], v[206:207]
	v_pk_fma_f32 v[44:45], v[44:45], v[160:161], v[208:209]
	v_pk_fma_f32 v[38:39], v[38:39], v[162:163], v[142:143]
	v_pk_fma_f32 v[40:41], v[40:41], v[164:165], v[144:145]
	v_pk_fma_f32 v[34:35], v[34:35], v[166:167], v[146:147]
	v_pk_fma_f32 v[36:37], v[36:37], v[168:169], v[148:149]
	global_store_dwordx4 v211, v[46:49], s[20:21]
	global_store_dwordx4 v211, v[42:45], s[20:21] offset:64
	global_store_dwordx4 v211, v[38:41], s[20:21] offset:512
	global_store_dwordx4 v211, v[34:37], s[20:21] offset:576
	s_waitcnt vmcnt(12)
	v_pk_fma_f32 v[30:31], v[30:31], v[154:155], v[170:171]
	v_pk_fma_f32 v[32:33], v[32:33], v[156:157], v[172:173]
	v_pk_fma_f32 v[26:27], v[26:27], v[158:159], v[174:175]
	v_pk_fma_f32 v[28:29], v[28:29], v[160:161], v[176:177]
	v_pk_fma_f32 v[22:23], v[22:23], v[162:163], v[178:179]
	v_pk_fma_f32 v[24:25], v[24:25], v[164:165], v[180:181]
	v_pk_fma_f32 v[18:19], v[18:19], v[166:167], v[182:183]
	v_pk_fma_f32 v[20:21], v[20:21], v[168:169], v[184:185]
	global_store_dwordx4 v220, v[30:33], s[20:21]
	global_store_dwordx4 v220, v[26:29], s[20:21] offset:64
	global_store_dwordx4 v220, v[22:25], s[20:21] offset:512
	global_store_dwordx4 v220, v[18:21], s[20:21] offset:576
	s_waitcnt vmcnt(8)
	v_pk_fma_f32 v[14:15], v[14:15], v[154:155], v[186:187]
	v_pk_fma_f32 v[16:17], v[16:17], v[156:157], v[188:189]
	v_pk_fma_f32 v[10:11], v[10:11], v[158:159], v[190:191]
	v_pk_fma_f32 v[12:13], v[12:13], v[160:161], v[192:193]
	v_pk_fma_f32 v[6:7], v[6:7], v[162:163], v[194:195]
	v_pk_fma_f32 v[8:9], v[8:9], v[164:165], v[196:197]
	v_pk_fma_f32 v[2:3], v[2:3], v[166:167], v[198:199]
	v_pk_fma_f32 v[4:5], v[4:5], v[168:169], v[200:201]
	global_store_dwordx4 v139, v[14:17], s[20:21]
	global_store_dwordx4 v139, v[10:13], s[20:21] offset:64
	global_store_dwordx4 v139, v[6:9], s[20:21] offset:512
	global_store_dwordx4 v139, v[2:5], s[20:21] offset:576
	v_mov_b32_e32 v170, v219
	s_mov_b32 s14, s0
	s_mov_b32 s16, s8
	s_mov_b64 s[20:21], s[12:13]
	s_mov_b64 s[18:19], s[10:11]
	s_and_b64 vcc, exec, s[4:5]
	s_cbranch_vccnz .LBB0_1156
	s_branch .LBB0_1120
